# adds: nt cache policy on the attention-merge row loads and the mLSTM output-pass row loads
# baseline (speedup 1.0000x reference)
; #define LAS __attribute__((address_space(3)))
; DI unsigned pk2(float lo, float hi) { f32x2n v = {lo, hi}; bf16x2n b = __builtin_convertvector(v, bf16x2n); return __builtin_bit_cast(unsigned, b); }
; template <bool P2>
; DI void ml_pass(LAS unsigned char* lds, const bf16_t* PROJ, const float* GATES, float* STATE, float* SC, bf16_t* YM,
;                 const float* convw, const float* convb, const float* ogain, int G, int bid) {
;     ...
;             const float wk = __expf(b_last + gq - m_new);
;             const float mt = fmaxf(bcum + m_prev, bcum + pm);
;             const float inter = __expf(bcum + m_prev - mt);
;             if (w == 0) gs[lane] = gq;
;             const int sp = tid & 31, pc = tid >> 5;
;             {
;                 u32x4 xr[5];
;                 const bf16_t* kb = PROJ + (row0 + 2 * sp) * 3072 + 512 + 128 * h + 8 * pc;
; #pragma unroll
;                 for (int r = 0; r < 5; ++r) { const int tt = t0 + 2 * sp - 3 + r; xr[r] = (tt >= 0) ? *(const u32x4*)(kb + ((long)r - 3) * 3072) : (u32x4){0u, 0u, 0u, 0u}; }
;                 float y0[8], y1[8]; conv2(xr, cw + 640, 8 * pc, y0, y1);
;                 if (P2) { u32x4 o; o.x = pk2(y0[0], y0[1]); o.y = pk2(y0[2], y0[3]); o.z = pk2(y0[4], y0[5]); o.w = pk2(y0[6], y0[7]); *(LAS u32x4*)(Ks + (2 * sp) * 136 + 8 * pc) = o;
;                     o.x = pk2(y1[0], y1[1]); o.y = pk2(y1[2], y1[3]); o.z = pk2(y1[4], y1[5]); o.w = pk2(y1[6], y1[7]); *(LAS u32x4*)(Ks + (2 * sp + 1) * 136 + 8 * pc) = o; }
;                 const float wk0 = __shfl(wk, 2 * sp), wk1 = __shfl(wk, 2 * sp + 1);
.LBB0_136:
	v_and_b32_e32 v135, 31, v133
	v_lshlrev_b32_e32 v138, 1, v135
	v_or_b32_e32 v66, s60, v138
	v_mov_b64_e32 v[64:65], s[28:29]
	v_mad_u64_u32 v[106:107], s[46:47], v66, s79, v[64:65]
	v_ashrrev_i32_e32 v65, 2, v133
	v_mad_i32_i24 v107, s61, v231, v107
	v_and_b32_e32 v108, -8, v65
	v_lshl_add_u64 v[66:67], v[106:107], 0, s[34:35]
	v_ashrrev_i32_e32 v109, 31, v108
	v_or_b32_e32 v64, s0, v138
	v_lshl_add_u64 v[110:111], v[108:109], 1, v[66:67]
	v_cmp_lt_u32_e64 s[48:49], 2, v64
	v_mov_b32_e32 v66, 0
	v_mov_b32_e32 v70, 0
	v_mov_b32_e32 v71, 0
	v_mov_b32_e32 v72, 0
	v_mov_b32_e32 v73, 0
	s_and_saveexec_b64 s[0:1], s[48:49]
	s_cbranch_execz .LBB0_138
	v_add_co_u32_e32 v68, vcc, 0xffffc000, v110
	s_nop 1
	v_addc_co_u32_e32 v69, vcc, -1, v111, vcc
	global_load_dwordx4 v[70:73], v[68:69], off offset:-1024 nt
.LBB0_138:
	s_or_b64 exec, exec, s[0:1]
	v_cmp_ne_u32_e64 s[46:47], 0, v64
	v_mov_b32_e32 v67, 0
	v_mov_b32_e32 v68, 0
	v_mov_b32_e32 v69, 0
	s_and_saveexec_b64 s[0:1], s[46:47]
	s_cbranch_execz .LBB0_140
	v_add_co_u32_e32 v66, vcc, 0xffffe000, v110
	s_nop 1
	v_addc_co_u32_e32 v67, vcc, -1, v111, vcc
	global_load_dwordx4 v[66:69], v[66:67], off offset:-3072 nt
.LBB0_140:
	s_or_b64 exec, exec, s[0:1]
	v_mov_b32_e32 v64, 0
	v_mov_b32_e32 v74, 0
	v_mov_b32_e32 v75, 0
	v_mov_b32_e32 v76, 0
	v_mov_b32_e32 v77, 0
	s_and_saveexec_b64 s[0:1], s[46:47]
	s_cbranch_execz .LBB0_142
	v_add_co_u32_e32 v74, vcc, 0xfffff000, v110
	s_nop 1
	v_addc_co_u32_e32 v75, vcc, -1, v111, vcc
	global_load_dwordx4 v[74:77], v[74:75], off offset:-1024 nt
.LBB0_142:
	s_or_b64 exec, exec, s[0:1]
	s_waitcnt lgkmcnt(0)
	global_load_dwordx4 v[86:89], v[110:111], off offset:1024 nt
	v_mov_b32_e32 v79, s78
	v_add_f32_e32 v109, s2, v112
	v_add_f32_e32 v79, s2, v79
	v_max_f32_e32 v132, v109, v79
	v_add_f32_e32 v78, s2, v78
	v_sub_f32_e32 v78, v78, v132
	v_mul_f32_e32 v78, 0x3fb8aa3b, v78
	v_exp_f32_e32 v140, v78
	v_add_co_u32_e32 v78, vcc, s37, v110
	v_lshl_add_u32 v139, v108, 2, 0
	s_nop 0
	v_addc_co_u32_e32 v79, vcc, 0, v111, vcc
	global_load_dwordx4 v[78:81], v[78:79], off offset:3072 nt
	v_add_u32_e32 v102, 0x22000, v139
	ds_read_b128 v[90:93], v102
	ds_read_b128 v[82:85], v102 offset:16
	ds_read_b128 v[94:97], v102 offset:2048
	ds_read_b128 v[98:101], v102 offset:512
	ds_read_b128 v[124:127], v102 offset:1024
	ds_read_b128 v[142:145], v102 offset:1536
	s_waitcnt vmcnt(2)
	v_lshlrev_b32_e32 v104, 16, v70
	v_and_b32_e32 v105, 0xffff0000, v70
	v_lshlrev_b32_e32 v146, 16, v66
	v_and_b32_e32 v147, 0xffff0000, v66
	s_waitcnt lgkmcnt(0)
	v_pk_fma_f32 v[104:105], v[90:91], v[104:105], v[94:95]
	v_lshlrev_b32_e32 v148, 16, v74
	v_and_b32_e32 v149, 0xffff0000, v74
	v_pk_fma_f32 v[104:105], v[98:99], v[146:147], v[104:105]
	v_pk_fma_f32 v[90:91], v[90:91], v[146:147], v[94:95]
	v_pk_fma_f32 v[104:105], v[124:125], v[148:149], v[104:105]
	v_pk_fma_f32 v[90:91], v[98:99], v[148:149], v[90:91]
	v_lshlrev_b32_e32 v70, 16, v71
	v_and_b32_e32 v71, 0xffff0000, v71
	v_lshlrev_b32_e32 v74, 16, v75
	v_and_b32_e32 v75, 0xffff0000, v75
	s_movk_i32 s0, 0xfde4
	v_or_b32_e32 v65, 7, v65
	s_waitcnt vmcnt(1)
	v_lshlrev_b32_e32 v150, 16, v86
	v_and_b32_e32 v151, 0xffff0000, v86
	v_pk_fma_f32 v[104:105], v[142:143], v[150:151], v[104:105]
	v_pk_fma_f32 v[90:91], v[124:125], v[150:151], v[90:91]
	v_mul_f32_e32 v66, 0xbfb8aa3b, v104
	v_exp_f32_e32 v66, v66
	v_lshlrev_b32_e32 v86, 16, v87
	v_and_b32_e32 v87, 0xffff0000, v87
	v_add_f32_e32 v66, 1.0, v66
	v_rcp_f32_e32 v122, v66
	v_mul_f32_e32 v66, 0xbfb8aa3b, v105
	v_exp_f32_e32 v66, v66
	s_nop 0
	v_add_f32_e32 v66, 1.0, v66
	v_rcp_f32_e32 v123, v66
	s_nop 0
	v_pk_mul_f32 v[122:123], v[104:105], v[122:123]
	s_waitcnt vmcnt(0)
	v_lshlrev_b32_e32 v104, 16, v78
	v_and_b32_e32 v105, 0xffff0000, v78
	v_pk_fma_f32 v[90:91], v[142:143], v[104:105], v[90:91]
	s_nop 0
	v_mul_f32_e32 v66, 0xbfb8aa3b, v90
	v_exp_f32_e32 v66, v66
	s_nop 0
	v_add_f32_e32 v66, 1.0, v66
	v_rcp_f32_e32 v94, v66
	v_mul_f32_e32 v66, 0xbfb8aa3b, v91
	v_exp_f32_e32 v66, v66
	s_nop 0
	v_add_f32_e32 v66, 1.0, v66
	v_rcp_f32_e32 v95, v66
	s_nop 0
	v_pk_mul_f32 v[124:125], v[90:91], v[94:95]
	v_lshlrev_b32_e32 v90, 16, v67
	v_and_b32_e32 v91, 0xffff0000, v67
	v_pk_fma_f32 v[66:67], v[92:93], v[70:71], v[96:97]
	s_nop 0
	v_pk_fma_f32 v[66:67], v[100:101], v[90:91], v[66:67]
	s_nop 0
	v_pk_fma_f32 v[66:67], v[126:127], v[74:75], v[66:67]
	s_nop 0
	v_pk_fma_f32 v[66:67], v[144:145], v[86:87], v[66:67]
	s_nop 0
	v_mul_f32_e32 v70, 0xbfb8aa3b, v66
	v_mul_f32_e32 v71, 0xbfb8aa3b, v67
	v_exp_f32_e32 v70, v70
	v_exp_f32_e32 v71, v71
	v_add_f32_e32 v70, 1.0, v70
	v_add_f32_e32 v71, 1.0, v71
	v_rcp_f32_e32 v70, v70
	v_rcp_f32_e32 v71, v71
	s_nop 0
	v_pk_mul_f32 v[66:67], v[66:67], v[70:71]
	v_lshlrev_b32_e32 v70, 16, v79
	v_and_b32_e32 v71, 0xffff0000, v79
	v_pk_fma_f32 v[78:79], v[92:93], v[90:91], v[96:97]
	s_nop 0
	v_pk_fma_f32 v[74:75], v[100:101], v[74:75], v[78:79]
	ds_read_b128 v[90:93], v102 offset:2064
	ds_read_b128 v[94:97], v102 offset:528
	ds_read_b128 v[98:101], v102 offset:1040
	ds_read_b128 v[102:105], v102 offset:1552
	v_pk_fma_f32 v[74:75], v[126:127], v[86:87], v[74:75]
	v_lshlrev_b32_e32 v126, 16, v72
	v_pk_fma_f32 v[70:71], v[144:145], v[70:71], v[74:75]
	v_and_b32_e32 v127, 0xffff0000, v72
	v_mul_f32_e32 v74, 0xbfb8aa3b, v70
	v_mul_f32_e32 v75, 0xbfb8aa3b, v71
	v_exp_f32_e32 v74, v74
	v_exp_f32_e32 v75, v75
	s_waitcnt lgkmcnt(3)
	v_pk_fma_f32 v[126:127], v[82:83], v[126:127], v[90:91]
	v_lshlrev_b32_e32 v78, 16, v76
	v_add_f32_e32 v74, 1.0, v74
	v_add_f32_e32 v75, 1.0, v75
	v_rcp_f32_e32 v74, v74
	v_rcp_f32_e32 v75, v75
	v_and_b32_e32 v79, 0xffff0000, v76
	v_lshlrev_b32_e32 v86, 16, v88
	v_and_b32_e32 v87, 0xffff0000, v88
	v_pk_mul_f32 v[70:71], v[70:71], v[74:75]
	v_lshlrev_b32_e32 v74, 16, v68
	v_and_b32_e32 v75, 0xffff0000, v68
	s_waitcnt lgkmcnt(2)
; #define LAS __attribute__((address_space(3)))
; DI unsigned pk2(float lo, float hi) { f32x2n v = {lo, hi}; bf16x2n b = __builtin_convertvector(v, bf16x2n); return __builtin_bit_cast(unsigned, b); }
; template <bool P2>
; DI void ml_pass(LAS unsigned char* lds, const bf16_t* PROJ, const float* GATES, float* STATE, float* SC, bf16_t* YM,
;                 const float* convw, const float* convb, const float* ogain, int G, int bid) {
;     ...
;                 if (P2) { u32x4 o; o.x = pk2(y0[0], y0[1]); o.y = pk2(y0[2], y0[3]); o.z = pk2(y0[4], y0[5]); o.w = pk2(y0[6], y0[7]); *(LAS u32x4*)(Ks + (2 * sp) * 136 + 8 * pc) = o;
;                     o.x = pk2(y1[0], y1[1]); o.y = pk2(y1[2], y1[3]); o.z = pk2(y1[4], y1[5]); o.w = pk2(y1[6], y1[7]); *(LAS u32x4*)(Ks + (2 * sp + 1) * 136 + 8 * pc) = o; }
;                 const float wk0 = __shfl(wk, 2 * sp), wk1 = __shfl(wk, 2 * sp + 1);
; #pragma unroll
;                 for (int j = 0; j < 8; ++j) Kt32[(8 * pc + j) * 36 + sp] = pk2(y0[j] * wk0, y1[j] * wk1);
;                 asm volatile("" ::: "memory");
;                 if (P2) {
;                     const bf16_t* qb = PROJ + (row0 + 2 * sp) * 3072 + 128 * h + 8 * pc;
; #pragma unroll
;                     for (int r = 0; r < 5; ++r) { const int tt = t0 + 2 * sp - 3 + r; xr[r] = (tt >= 0) ? *(const u32x4*)(qb + ((long)r - 3) * 3072) : (u32x4){0u, 0u, 0u, 0u}; }
	v_pk_fma_f32 v[126:127], v[94:95], v[74:75], v[126:127]
	v_pk_fma_f32 v[74:75], v[82:83], v[74:75], v[90:91]
	s_waitcnt lgkmcnt(1)
	v_pk_fma_f32 v[126:127], v[98:99], v[78:79], v[126:127]
	v_pk_fma_f32 v[74:75], v[94:95], v[78:79], v[74:75]
	s_waitcnt lgkmcnt(0)
	v_pk_fma_f32 v[126:127], v[102:103], v[86:87], v[126:127]
	v_pk_fma_f32 v[74:75], v[98:99], v[86:87], v[74:75]
	v_mul_f32_e32 v68, 0xbfb8aa3b, v126
	v_exp_f32_e32 v68, v68
	v_lshlrev_b32_e32 v72, 16, v73
	v_and_b32_e32 v73, 0xffff0000, v73
	v_pk_fma_f32 v[72:73], v[84:85], v[72:73], v[92:93]
	v_add_f32_e32 v68, 1.0, v68
	v_rcp_f32_e32 v142, v68
	v_mul_f32_e32 v68, 0xbfb8aa3b, v127
	v_exp_f32_e32 v68, v68
	v_lshlrev_b32_e32 v76, 16, v89
	v_add_f32_e32 v68, 1.0, v68
	v_rcp_f32_e32 v143, v68
	s_nop 0
	v_pk_mul_f32 v[142:143], v[126:127], v[142:143]
	v_lshlrev_b32_e32 v126, 16, v80
	v_and_b32_e32 v127, 0xffff0000, v80
	v_pk_fma_f32 v[74:75], v[102:103], v[126:127], v[74:75]
	v_and_b32_e32 v126, 64, v232
	v_mul_f32_e32 v68, 0xbfb8aa3b, v74
	v_exp_f32_e32 v68, v68
	s_nop 0
	v_add_f32_e32 v68, 1.0, v68
	v_rcp_f32_e32 v78, v68
	v_mul_f32_e32 v68, 0xbfb8aa3b, v75
	v_exp_f32_e32 v68, v68
	s_nop 0
	v_add_f32_e32 v68, 1.0, v68
	v_rcp_f32_e32 v79, v68
	v_lshlrev_b32_e32 v68, 16, v69
	v_and_b32_e32 v69, 0xffff0000, v69
	v_pk_fma_f32 v[72:73], v[96:97], v[68:69], v[72:73]
	v_pk_mul_f32 v[78:79], v[74:75], v[78:79]
	v_lshlrev_b32_e32 v74, 16, v77
	v_and_b32_e32 v75, 0xffff0000, v77
	v_and_b32_e32 v77, 0xffff0000, v89
	v_pk_fma_f32 v[72:73], v[100:101], v[74:75], v[72:73]
	v_pk_fma_f32 v[68:69], v[84:85], v[68:69], v[92:93]
	v_pk_fma_f32 v[72:73], v[104:105], v[76:77], v[72:73]
	v_pk_fma_f32 v[68:69], v[96:97], v[74:75], v[68:69]
	v_mul_f32_e32 v80, 0xbfb8aa3b, v72
	v_exp_f32_e32 v80, v80
	v_pk_fma_f32 v[68:69], v[100:101], v[76:77], v[68:69]
	v_lshlrev_b32_e32 v77, 1, v108
	v_cvt_pk_bf16_f32 v74, v142, v143
	v_add_f32_e32 v80, 1.0, v80
	v_rcp_f32_e32 v82, v80
	v_mul_f32_e32 v80, 0xbfb8aa3b, v73
	v_exp_f32_e32 v80, v80
	s_nop 0
	v_add_f32_e32 v80, 1.0, v80
	v_rcp_f32_e32 v83, v80
	v_mul_u32_u24_e32 v80, 0x110, v135
	v_lshl_add_u32 v76, v80, 1, 0
	v_pk_mul_f32 v[82:83], v[72:73], v[82:83]
	v_lshlrev_b32_e32 v72, 16, v81
	v_and_b32_e32 v73, 0xffff0000, v81
	v_pk_fma_f32 v[68:69], v[104:105], v[72:73], v[68:69]
	v_cvt_pk_bf16_f32 v75, v82, v83
	v_mul_f32_e32 v72, 0xbfb8aa3b, v68
	v_mul_f32_e32 v73, 0xbfb8aa3b, v69
	v_exp_f32_e32 v72, v72
	v_exp_f32_e32 v73, v73
	v_add_u32_e32 v81, v76, v77
	v_mad_i32_i24 v76, v135, s0, v76
	v_add_f32_e32 v72, 1.0, v72
	v_add_f32_e32 v73, 1.0, v73
	v_rcp_f32_e32 v72, v72
	v_rcp_f32_e32 v73, v73
	s_nop 0
	v_pk_mul_f32 v[68:69], v[68:69], v[72:73]
	v_cvt_pk_bf16_f32 v72, v122, v123
	v_cvt_pk_bf16_f32 v73, v66, v67
	ds_write_b128 v81, v[72:75] offset:17408
	v_or_b32_e32 v81, 1, v138
	v_mul_u32_u24_e32 v84, 0x88, v81
	v_lshlrev_b32_e32 v84, 1, v84
	v_cvt_pk_bf16_f32 v72, v124, v125
	v_cvt_pk_bf16_f32 v73, v70, v71
	v_cvt_pk_bf16_f32 v74, v78, v79
	v_cvt_pk_bf16_f32 v75, v68, v69
	v_add3_u32 v77, 0, v84, v77
	ds_write_b128 v77, v[72:75] offset:17408
	v_or_b32_e32 v72, v126, v138
	v_or_b32_e32 v73, v126, v81
	v_lshlrev_b32_e32 v72, 2, v72
	v_lshlrev_b32_e32 v73, 2, v73
	ds_bpermute_b32 v72, v72, v140
	ds_bpermute_b32 v73, v73, v140
	v_mov_b32_e32 v74, v122
	v_mov_b32_e32 v75, v124
	v_mov_b32_e32 v124, v123
	s_waitcnt lgkmcnt(0)
	v_pk_mul_f32 v[74:75], v[74:75], v[72:73]
	s_nop 0
	v_cvt_pk_bf16_f32 v81, v74, v75
	v_mad_u64_u32 v[74:75], s[0:1], v108, s25, v[76:77]
	v_pk_mul_f32 v[84:85], v[124:125], v[72:73]
	v_add_u32_e32 v86, 0x8800, v74
	v_cvt_pk_bf16_f32 v75, v84, v85
	v_mov_b32_e32 v84, v66
	v_mov_b32_e32 v85, v70
	v_mov_b32_e32 v70, v67
	v_pk_mul_f32 v[84:85], v[84:85], v[72:73]
	v_pk_mul_f32 v[66:67], v[70:71], v[72:73]
	ds_write2_b32 v86, v81, v75 offset1:36
	v_cvt_pk_bf16_f32 v75, v84, v85
	v_cvt_pk_bf16_f32 v66, v66, v67
	ds_write2_b32 v86, v75, v66 offset0:72 offset1:108
	v_mov_b32_e32 v66, v142
	v_mov_b32_e32 v67, v78
	v_pk_mul_f32 v[66:67], v[66:67], v[72:73]
	v_mov_b32_e32 v78, v143
	v_cvt_pk_bf16_f32 v70, v66, v67
	v_pk_mul_f32 v[66:67], v[78:79], v[72:73]
	s_nop 0
	v_cvt_pk_bf16_f32 v66, v66, v67
	ds_write2_b32 v86, v70, v66 offset0:144 offset1:180
	v_mov_b32_e32 v66, v82
	v_mov_b32_e32 v67, v68
	v_pk_mul_f32 v[66:67], v[66:67], v[72:73]
	v_mov_b32_e32 v68, v83
	v_cvt_pk_bf16_f32 v66, v66, v67
	ds_write_b32 v74, v66 offset:35680
	v_pk_mul_f32 v[66:67], v[68:69], v[72:73]
	s_nop 0
	v_cvt_pk_bf16_f32 v68, v66, v67
	v_mad_u64_u32 v[66:67], s[0:1], v65, s25, v[76:77]
	ds_write_b32 v66, v68 offset:34816
	v_mov_b32_e32 v65, 0
	v_mov_b32_e32 v66, 0
	v_mov_b32_e32 v67, 0
	s_and_saveexec_b64 s[0:1], s[48:49]
	s_cbranch_execz .LBB0_144
	v_add_co_u32_e32 v64, vcc, 0xffffc000, v110
	s_nop 1
	v_addc_co_u32_e32 v65, vcc, -1, v111, vcc
	global_load_dwordx4 v[64:67], v[64:65], off offset:-2048 nt
.LBB0_144:
	s_or_b64 exec, exec, s[0:1]
	v_mov_b32_e32 v68, 0
	v_mov_b32_e32 v72, 0
	v_mov_b32_e32 v73, 0
	v_mov_b32_e32 v74, 0
	v_mov_b32_e32 v75, 0
	s_and_saveexec_b64 s[0:1], s[46:47]
	s_cbranch_execz .LBB0_146
	v_add_co_u32_e32 v70, vcc, 0xffffd000, v110
	s_nop 1
	v_addc_co_u32_e32 v71, vcc, -1, v111, vcc
	global_load_dwordx4 v[72:75], v[70:71], off nt
.LBB0_146:
	s_or_b64 exec, exec, s[0:1]
	v_mov_b32_e32 v69, 0
	v_mov_b32_e32 v70, 0
	v_mov_b32_e32 v71, 0
	s_and_saveexec_b64 s[0:1], s[46:47]
	s_cbranch_execz .LBB0_148
	v_add_co_u32_e32 v68, vcc, 0xfffff000, v110
	s_nop 1
	v_addc_co_u32_e32 v69, vcc, -1, v111, vcc
	global_load_dwordx4 v[68:71], v[68:69], off offset:-2048 nt
; #define LAS __attribute__((address_space(3)))
; DI unsigned pk2(float lo, float hi) { f32x2n v = {lo, hi}; bf16x2n b = __builtin_convertvector(v, bf16x2n); return __builtin_bit_cast(unsigned, b); }
; DI float silu(float y) { return y * frcp(1.0f + __expf(-y)); }
; DI void conv2(const u32x4 (&x)[5], const LAS float* cw, int dd, float (&y0)[8], float (&y1)[8]) {
;     float xf[5][8];
; #pragma unroll
;     for (int r = 0; r < 5; ++r) { xf[r][0] = bflo(x[r].x); xf[r][1] = bfhi(x[r].x); xf[r][2] = bflo(x[r].y); xf[r][3] = bfhi(x[r].y); xf[r][4] = bflo(x[r].z); xf[r][5] = bfhi(x[r].z); xf[r][6] = bflo(x[r].w); xf[r][7] = bfhi(x[r].w); }
; #pragma unroll
;     for (int j = 0; j < 8; ++j) { const float b = cw[4 * 128 + dd + j]; float a0 = b, a1 = b;
; #pragma unroll
;         for (int tp = 0; tp < 4; ++tp) { const float c = cw[tp * 128 + dd + j]; a0 += xf[tp][j] * c; a1 += xf[tp + 1][j] * c; }
;         y0[j] = silu(a0); y1[j] = silu(a1); }
; template <bool P2>
; DI void ml_pass(LAS unsigned char* lds, const bf16_t* PROJ, const float* GATES, float* STATE, float* SC, bf16_t* YM,
;                 const float* convw, const float* convb, const float* ogain, int G, int bid) {
;     ...
;                     for (int r = 0; r < 5; ++r) { const int tt = t0 + 2 * sp - 3 + r; xr[r] = (tt >= 0) ? *(const u32x4*)(qb + ((long)r - 3) * 3072) : (u32x4){0u, 0u, 0u, 0u}; }
;                     conv2(xr, cw, 8 * pc, y0, y1);
;                     const float qs = 0.08838834764831845f;
;                     u32x4 o; o.x = pk2(y0[0] * qs, y0[1] * qs); o.y = pk2(y0[2] * qs, y0[3] * qs); o.z = pk2(y0[4] * qs, y0[5] * qs); o.w = pk2(y0[6] * qs, y0[7] * qs); *(LAS u32x4*)(Qs + (2 * sp) * 136 + 8 * pc) = o;
;                     o.x = pk2(y1[0] * qs, y1[1] * qs); o.y = pk2(y1[2] * qs, y1[3] * qs); o.z = pk2(y1[4] * qs, y1[5] * qs); o.w = pk2(y1[6] * qs, y1[7] * qs); *(LAS u32x4*)(Qs + (2 * sp + 1) * 136 + 8 * pc) = o;
.LBB0_148:
	s_or_b64 exec, exec, s[0:1]
	global_load_dwordx4 v[82:85], v[110:111], off nt
	v_add_co_u32_e32 v78, vcc, 0x1000, v110
	s_waitcnt vmcnt(1)
	v_lshlrev_b32_e32 v146, 16, v64
	v_addc_co_u32_e32 v79, vcc, 0, v111, vcc
	v_and_b32_e32 v147, 0xffff0000, v64
	v_lshlrev_b32_e32 v152, 16, v65
	v_and_b32_e32 v153, 0xffff0000, v65
	v_lshlrev_b32_e32 v158, 16, v66
	v_and_b32_e32 v159, 0xffff0000, v66
	v_lshlrev_b32_e32 v164, 16, v67
	v_and_b32_e32 v165, 0xffff0000, v67
	global_load_dwordx4 v[64:67], v[78:79], off offset:2048 nt
	v_add_u32_e32 v110, 0x21600, v139
	v_lshlrev_b32_e32 v148, 16, v72
	v_and_b32_e32 v149, 0xffff0000, v72
	v_lshlrev_b32_e32 v150, 16, v68
	v_and_b32_e32 v151, 0xffff0000, v68
	v_lshlrev_b32_e32 v154, 16, v73
	v_and_b32_e32 v155, 0xffff0000, v73
	v_lshlrev_b32_e32 v156, 16, v69
	v_and_b32_e32 v157, 0xffff0000, v69
	v_lshlrev_b32_e32 v160, 16, v74
	v_and_b32_e32 v161, 0xffff0000, v74
	v_lshlrev_b32_e32 v162, 16, v70
	v_and_b32_e32 v163, 0xffff0000, v70
	v_lshlrev_b32_e32 v166, 16, v75
	v_and_b32_e32 v167, 0xffff0000, v75
	v_lshlrev_b32_e32 v168, 16, v71
	v_and_b32_e32 v169, 0xffff0000, v71
	ds_read_b128 v[68:71], v110
	ds_read_b128 v[72:75], v110 offset:16
	ds_read_b128 v[86:89], v110 offset:2048
	ds_read_b128 v[90:93], v110 offset:2064
	ds_read_b128 v[94:97], v110 offset:512
	ds_read_b128 v[98:101], v110 offset:528
	ds_read_b128 v[102:105], v110 offset:1024
	ds_read_b128 v[122:125], v110 offset:1040
	ds_read_b128 v[138:141], v110 offset:1536
	ds_read_b128 v[142:145], v110 offset:1552
	s_waitcnt lgkmcnt(7)
	v_pk_fma_f32 v[78:79], v[68:69], v[146:147], v[86:87]
	v_pk_fma_f32 v[110:111], v[70:71], v[152:153], v[88:89]
	s_waitcnt lgkmcnt(5)
	v_pk_fma_f32 v[78:79], v[94:95], v[148:149], v[78:79]
	v_pk_fma_f32 v[146:147], v[72:73], v[158:159], v[90:91]
	v_pk_fma_f32 v[110:111], v[96:97], v[154:155], v[110:111]
	s_waitcnt lgkmcnt(3)
	v_pk_fma_f32 v[78:79], v[102:103], v[150:151], v[78:79]
	v_pk_fma_f32 v[152:153], v[74:75], v[164:165], v[92:93]
	v_pk_fma_f32 v[146:147], v[98:99], v[160:161], v[146:147]
	v_pk_fma_f32 v[110:111], v[104:105], v[156:157], v[110:111]
	s_waitcnt lgkmcnt(2)
	v_pk_fma_f32 v[146:147], v[122:123], v[162:163], v[146:147]
	v_pk_fma_f32 v[152:153], v[100:101], v[166:167], v[152:153]
	v_pk_fma_f32 v[68:69], v[68:69], v[148:149], v[86:87]
	s_movk_i32 s0, 0x21c
	v_pk_fma_f32 v[68:69], v[94:95], v[150:151], v[68:69]
	v_mad_u32_u24 v76, v135, s0, v76
	v_pk_fma_f32 v[70:71], v[70:71], v[154:155], v[88:89]
	v_lshl_add_u32 v108, v108, 1, v76
	v_pk_fma_f32 v[70:71], v[96:97], v[156:157], v[70:71]
	v_pk_fma_f32 v[72:73], v[72:73], v[160:161], v[90:91]
	v_mul_i32_i24_e32 v81, 0xfffffde4, v135
	v_pk_fma_f32 v[72:73], v[98:99], v[162:163], v[72:73]
	s_lshl_b32 s46, s75, 1
	s_mov_b32 s47, s35
	s_mov_b32 s2, 0
	s_mov_b64 s[48:49], -1
	s_waitcnt vmcnt(1)
	v_lshlrev_b32_e32 v158, 16, v82
	v_and_b32_e32 v159, 0xffff0000, v82
	v_lshlrev_b32_e32 v164, 16, v83
	v_and_b32_e32 v165, 0xffff0000, v83
	s_waitcnt lgkmcnt(1)
	v_pk_fma_f32 v[78:79], v[138:139], v[158:159], v[78:79]
	v_lshlrev_b32_e32 v170, 16, v84
	v_and_b32_e32 v171, 0xffff0000, v84
	v_pk_fma_f32 v[82:83], v[140:141], v[164:165], v[110:111]
	v_mul_f32_e32 v110, 0xbfb8aa3b, v78
	v_mul_f32_e32 v111, 0xbfb8aa3b, v79
	v_lshlrev_b32_e32 v172, 16, v85
	v_and_b32_e32 v173, 0xffff0000, v85
	s_waitcnt lgkmcnt(0)
	v_pk_fma_f32 v[84:85], v[142:143], v[170:171], v[146:147]
	v_mul_f32_e32 v127, 0xbfb8aa3b, v82
	v_mul_f32_e32 v146, 0xbfb8aa3b, v83
	v_exp_f32_e32 v110, v110
	v_exp_f32_e32 v111, v111
	v_mul_f32_e32 v147, 0xbfb8aa3b, v84
	v_exp_f32_e32 v127, v127
	v_exp_f32_e32 v146, v146
	v_exp_f32_e32 v147, v147
	v_add_f32_e32 v110, 1.0, v110
	v_add_f32_e32 v111, 1.0, v111
	v_add_f32_e32 v127, 1.0, v127
	v_add_f32_e32 v175, 1.0, v146
	v_rcp_f32_e32 v110, v110
	v_rcp_f32_e32 v111, v111
	v_add_f32_e32 v176, 1.0, v147
	v_rcp_f32_e32 v146, v127
	v_rcp_f32_e32 v147, v175
	v_pk_mul_f32 v[78:79], v[78:79], v[110:111]
	v_mul_f32_e32 v174, 0xbfb8aa3b, v85
	v_pk_mul_f32 v[78:79], v[78:79], s[36:37] op_sel_hi:[1,0]
	v_pk_mul_f32 v[82:83], v[82:83], v[146:147]
	v_exp_f32_e32 v174, v174
	v_pk_mul_f32 v[110:111], v[82:83], s[36:37] op_sel_hi:[1,0]
	v_cvt_pk_bf16_f32 v82, v78, v79
	v_pk_fma_f32 v[78:79], v[124:125], v[168:169], v[152:153]
	v_cvt_pk_bf16_f32 v83, v110, v111
	v_pk_fma_f32 v[78:79], v[144:145], v[172:173], v[78:79]
	v_add_f32_e32 v127, 1.0, v174
	v_mul_f32_e32 v110, 0xbfb8aa3b, v78
	v_mul_f32_e32 v111, 0xbfb8aa3b, v79
	v_exp_f32_e32 v110, v110
	v_exp_f32_e32 v111, v111
	v_rcp_f32_e32 v174, v176
	v_rcp_f32_e32 v175, v127
	v_add_f32_e32 v110, 1.0, v110
	v_add_f32_e32 v111, 1.0, v111
	v_rcp_f32_e32 v110, v110
	v_rcp_f32_e32 v111, v111
	v_pk_mul_f32 v[84:85], v[84:85], v[174:175]
	v_pk_fma_f32 v[68:69], v[102:103], v[158:159], v[68:69]
	v_pk_mul_f32 v[84:85], v[84:85], s[36:37] op_sel_hi:[1,0]
	v_pk_mul_f32 v[78:79], v[78:79], v[110:111]
	v_cvt_pk_bf16_f32 v84, v84, v85
	v_pk_mul_f32 v[78:79], v[78:79], s[36:37] op_sel_hi:[1,0]
	v_pk_fma_f32 v[70:71], v[104:105], v[164:165], v[70:71]
	v_cvt_pk_bf16_f32 v85, v78, v79
	s_waitcnt vmcnt(0)
; #define LAS __attribute__((address_space(3)))
; DI unsigned pk2(float lo, float hi) { f32x2n v = {lo, hi}; bf16x2n b = __builtin_convertvector(v, bf16x2n); return __builtin_bit_cast(unsigned, b); }
; template <bool P2>
; DI void ml_pass(LAS unsigned char* lds, const bf16_t* PROJ, const float* GATES, float* STATE, float* SC, bf16_t* YM,
;                 const float* convw, const float* convb, const float* ogain, int G, int bid) {
;     ...
;                     conv2(xr, cw, 8 * pc, y0, y1);
;                     const float qs = 0.08838834764831845f;
;                     u32x4 o; o.x = pk2(y0[0] * qs, y0[1] * qs); o.y = pk2(y0[2] * qs, y0[3] * qs); o.z = pk2(y0[4] * qs, y0[5] * qs); o.w = pk2(y0[6] * qs, y0[7] * qs); *(LAS u32x4*)(Qs + (2 * sp) * 136 + 8 * pc) = o;
;                     o.x = pk2(y1[0] * qs, y1[1] * qs); o.y = pk2(y1[2] * qs, y1[3] * qs); o.z = pk2(y1[4] * qs, y1[5] * qs); o.w = pk2(y1[6] * qs, y1[7] * qs); *(LAS u32x4*)(Qs + (2 * sp + 1) * 136 + 8 * pc) = o;
	v_lshlrev_b32_e32 v78, 16, v64
	v_and_b32_e32 v79, 0xffff0000, v64
	v_pk_fma_f32 v[68:69], v[138:139], v[78:79], v[68:69]
	ds_write_b128 v108, v[82:85]
	v_mul_f32_e32 v78, 0xbfb8aa3b, v69
	v_exp_f32_e32 v78, v78
	v_and_b32_e32 v79, 0xffff0000, v65
	v_mul_f32_e32 v64, 0xbfb8aa3b, v68
	v_exp_f32_e32 v64, v64
	v_add_f32_e32 v82, 1.0, v78
	v_lshlrev_b32_e32 v78, 16, v65
	v_pk_fma_f32 v[70:71], v[140:141], v[78:79], v[70:71]
	v_add_f32_e32 v64, 1.0, v64
	v_mul_f32_e32 v65, 0xbfb8aa3b, v70
	v_exp_f32_e32 v78, v65
	v_mul_f32_e32 v65, 0xbfb8aa3b, v71
	v_exp_f32_e32 v79, v65
	v_rcp_f32_e32 v64, v64
	v_add_f32_e32 v78, 1.0, v78
	v_rcp_f32_e32 v65, v82
	v_add_f32_e32 v79, 1.0, v79
	v_rcp_f32_e32 v78, v78
	v_rcp_f32_e32 v79, v79
	v_pk_mul_f32 v[64:65], v[68:69], v[64:65]
	v_pk_fma_f32 v[72:73], v[122:123], v[170:171], v[72:73]
	v_pk_mul_f32 v[64:65], v[64:65], s[36:37] op_sel_hi:[1,0]
	v_pk_mul_f32 v[68:69], v[70:71], v[78:79]
	v_lshlrev_b32_e32 v70, 16, v66
	v_and_b32_e32 v71, 0xffff0000, v66
	v_pk_fma_f32 v[70:71], v[142:143], v[70:71], v[72:73]
	v_cvt_pk_bf16_f32 v64, v64, v65
	v_mul_f32_e32 v65, 0xbfb8aa3b, v70
	v_exp_f32_e32 v66, v65
	v_mul_f32_e32 v65, 0xbfb8aa3b, v71
	v_exp_f32_e32 v72, v65
	v_pk_mul_f32 v[68:69], v[68:69], s[36:37] op_sel_hi:[1,0]
	v_add_f32_e32 v66, 1.0, v66
	v_cvt_pk_bf16_f32 v65, v68, v69
	v_add_f32_e32 v78, 1.0, v72
	v_pk_fma_f32 v[72:73], v[74:75], v[166:167], v[92:93]
	v_lshlrev_b32_e32 v68, 16, v67
	v_pk_fma_f32 v[72:73], v[100:101], v[168:169], v[72:73]
	v_and_b32_e32 v69, 0xffff0000, v67
	v_pk_fma_f32 v[72:73], v[124:125], v[172:173], v[72:73]
	v_rcp_f32_e32 v66, v66
	v_pk_fma_f32 v[68:69], v[144:145], v[68:69], v[72:73]
	s_nop 0
	v_mul_f32_e32 v67, 0xbfb8aa3b, v68
	v_exp_f32_e32 v72, v67
	v_mul_f32_e32 v67, 0xbfb8aa3b, v69
	v_exp_f32_e32 v73, v67
	v_rcp_f32_e32 v67, v78
	v_add_f32_e32 v72, 1.0, v72
	v_rcp_f32_e32 v72, v72
	v_add_f32_e32 v73, 1.0, v73
	v_rcp_f32_e32 v73, v73
	v_pk_mul_f32 v[66:67], v[70:71], v[66:67]
	v_pk_mul_f32 v[68:69], v[68:69], v[72:73]
	v_pk_mul_f32 v[66:67], v[66:67], s[36:37] op_sel_hi:[1,0]
	v_pk_mul_f32 v[68:69], v[68:69], s[36:37] op_sel_hi:[1,0]
	v_cvt_pk_bf16_f32 v66, v66, v67
	v_cvt_pk_bf16_f32 v67, v68, v69
	ds_write_b128 v77, v[64:67]
	v_lshl_add_u64 v[64:65], v[106:107], 0, s[46:47]
	v_add_u32_e32 v66, v76, v81
; #define LAS __attribute__((address_space(3)))
; template <bool P2>
; DI void ml_pass(LAS unsigned char* lds, const bf16_t* PROJ, const float* GATES, float* STATE, float* SC, bf16_t* YM,
;                 const float* convw, const float* convb, const float* ogain, int G, int bid) {
;     ...
;             for (int it = 0; it < 2; ++it) { const int idx = tid + 512 * it, sp2 = idx & 31, pc2 = idx >> 5;
;                 const bf16_t* vb = PROJ + (row0 + 2 * sp2) * 3072 + 1024 + 256 * h + 8 * pc2;
;                 const u32x4 r0 = *(const u32x4*)vb, r1 = *(const u32x4*)(vb + 3072);
;                 LAS unsigned* dst = Vt32 + (8 * pc2) * 36 + sp2;
;                 dst[0 * 36] = (r0.x & 0xffffu) | (r1.x << 16); dst[1 * 36] = (r0.x >> 16) | (r1.x & 0xffff0000u);
;                 dst[2 * 36] = (r0.y & 0xffffu) | (r1.y << 16); dst[3 * 36] = (r0.y >> 16) | (r1.y & 0xffff0000u);
;                 dst[4 * 36] = (r0.z & 0xffffu) | (r1.z << 16); dst[5 * 36] = (r0.z >> 16) | (r1.z & 0xffff0000u);
;                 dst[6 * 36] = (r0.w & 0xffffu) | (r1.w << 16); dst[7 * 36] = (r0.w >> 16) | (r1.w & 0xffff0000u); }
;             lbar();
;             if (P2) {
;                 if (w < 4) {
;                     const int stl = w & 1, ttl = w >> 1; const int t = 32 * ttl + l31;
;                     float rowsum = 0.f;
;                     if (w == 1) {
; #pragma unroll
;                         for (int i4 = 0; i4 < 4; ++i4) *(LAS u32x2*)(Ws + t * 72 + 32 + 8 * i4 + 4 * hi) = (u32x2){0u, 0u};
;                     } else {
;                         f32x16 acc;
; #pragma unroll
;                         for (int i = 0; i < 16; ++i) acc[i] = 0.f;
; #pragma unroll
;                         for (int kq = 0; kq < 8; ++kq) { const bf16x8 a = *(const LAS bf16x8*)(Ks + (32 * stl + l31) * 136 + 16 * kq + 8 * hi), bb = *(const LAS bf16x8*)(Qs + t * 136 + 16 * kq + 8 * hi);
;                             acc = mfma32(a, bb, acc); }
;                         const float bc_t = __shfl(bcum, t), mt_t = __shfl(mt, t);
; #pragma unroll
;                         for (int i4 = 0; i4 < 4; ++i4) { const int s0 = 32 * stl + 8 * i4 + 4 * hi; const f32x4 g4 = *(const LAS f32x4*)(gs + s0); float v[4];
; #pragma unroll
;                             for (int e = 0; e < 4; ++e) { const int s = s0 + e; v[e] = (s <= t) ? acc[4 * i4 + e] * __expf(bc_t + g4[e] - mt_t) : 0.f; rowsum += v[e]; }
.LBB0_149:
	v_cndmask_b32_e64 v67, 0, 1, s[48:49]
	v_cmp_ne_u32_e64 s[0:1], 1, v67
	v_add_u32_e32 v67, s2, v133
	v_ashrrev_i32_e32 v67, 2, v67
	v_and_b32_e32 v76, -8, v67
	v_ashrrev_i32_e32 v77, 31, v76
	v_lshl_add_u64 v[72:73], v[76:77], 1, v[64:65]
	global_load_dwordx4 v[68:71], v[72:73], off offset:2048 nt
	v_add_co_u32_e32 v72, vcc, 0x2000, v72
	v_mad_u64_u32 v[76:77], s[48:49], v76, s25, v[66:67]
	s_nop 0
	v_addc_co_u32_e32 v73, vcc, 0, v73, vcc
	global_load_dwordx4 v[72:75], v[72:73], off nt
	s_movk_i32 s2, 0x200
	s_mov_b64 s[48:49], 0
	s_and_b64 vcc, exec, s[0:1]
	s_waitcnt vmcnt(1)
	v_and_b32_e32 v67, 0xffff, v68
	v_lshrrev_b32_e32 v68, 16, v68
	s_waitcnt vmcnt(0)
	v_lshl_or_b32 v67, v72, 16, v67
	v_and_or_b32 v68, v72, s27, v68
	v_add_u32_e32 v72, 0xd000, v76
	ds_write2_b32 v72, v67, v68 offset1:36
	v_and_b32_e32 v67, 0xffff, v69
	v_lshrrev_b32_e32 v68, 16, v69
	v_lshl_or_b32 v67, v73, 16, v67
	v_and_or_b32 v68, v73, s27, v68
	ds_write2_b32 v72, v67, v68 offset0:72 offset1:108
	v_and_b32_e32 v67, 0xffff, v70
	v_lshrrev_b32_e32 v68, 16, v70
	v_lshl_or_b32 v67, v74, 16, v67
	v_and_or_b32 v68, v74, s27, v68
	ds_write2_b32 v72, v67, v68 offset0:144 offset1:180
	v_and_b32_e32 v67, 0xffff, v71
	v_lshrrev_b32_e32 v68, 16, v71
	v_lshl_or_b32 v67, v75, 16, v67
	v_and_or_b32 v68, v75, s27, v68
	ds_write2_b32 v72, v67, v68 offset0:216 offset1:252
	s_cbranch_vccz .LBB0_149
	s_waitcnt lgkmcnt(0)
	s_barrier
	s_ashr_i32 s47, s77, 6
	s_cmp_gt_i32 s47, 3
	s_mov_b64 s[0:1], -1
	s_cbranch_scc0 .LBB0_154
	v_add_u32_e32 v64, 0xffffff00, v133
	v_ashrrev_i32_e32 v64, 2, v64
	v_and_b32_e32 v78, 3, v133
	v_mul_lo_u32 v65, v64, s24
	v_lshlrev_b32_e32 v66, 6, v78
	v_add3_u32 v65, 0, v65, v66
	ds_read_b128 v[66:69], v65
	ds_read_b128 v[70:73], v65 offset:16
	ds_read_b128 v[74:77], v65 offset:32
	ds_read_b128 v[82:85], v65 offset:48
	v_lshl_add_u32 v65, v78, 7, 0
	v_add_u32_e32 v65, 0x20800, v65
	ds_read_b128 v[86:89], v65
	ds_read_b128 v[90:93], v65 offset:16
	ds_read_b128 v[94:97], v65 offset:32
	ds_read_b128 v[98:101], v65 offset:48
	s_waitcnt lgkmcnt(7)
	v_lshlrev_b32_e32 v79, 16, v66
	v_and_b32_e32 v66, 0xffff0000, v66
	s_waitcnt lgkmcnt(3)
	v_mul_f32_e32 v66, v87, v66
	v_fmac_f32_e32 v66, v86, v79
	v_lshlrev_b32_e32 v79, 16, v67
	v_fmac_f32_e32 v66, v88, v79
	v_and_b32_e32 v67, 0xffff0000, v67
	v_fmac_f32_e32 v66, v89, v67
	v_lshlrev_b32_e32 v67, 16, v68
	s_waitcnt lgkmcnt(2)
	v_fmac_f32_e32 v66, v90, v67
	v_and_b32_e32 v67, 0xffff0000, v68
	v_fmac_f32_e32 v66, v91, v67
	v_lshlrev_b32_e32 v67, 16, v69
	v_fmac_f32_e32 v66, v92, v67
	v_and_b32_e32 v67, 0xffff0000, v69
	v_fmac_f32_e32 v66, v93, v67
	v_and_b32_e32 v67, 0xffff0000, v70
	v_add_f32_e32 v79, 0, v66
	v_lshlrev_b32_e32 v66, 16, v70
	s_waitcnt lgkmcnt(1)
	v_mul_f32_e32 v70, v95, v67
	v_fmac_f32_e32 v70, v94, v66
	v_lshlrev_b32_e32 v66, 16, v71
	v_fmac_f32_e32 v70, v96, v66
	v_and_b32_e32 v66, 0xffff0000, v71
	v_fmac_f32_e32 v70, v97, v66
	v_lshlrev_b32_e32 v66, 16, v72
	s_waitcnt lgkmcnt(0)
	v_fmac_f32_e32 v70, v98, v66
	v_and_b32_e32 v66, 0xffff0000, v72
	v_fmac_f32_e32 v70, v99, v66
	v_lshlrev_b32_e32 v66, 16, v73
	v_fmac_f32_e32 v70, v100, v66
	v_and_b32_e32 v66, 0xffff0000, v73
	v_fmac_f32_e32 v70, v101, v66
	ds_read_b128 v[66:69], v65 offset:64
	v_add_f32_e32 v79, v79, v70
	ds_read_b128 v[70:73], v65 offset:80
	v_lshlrev_b32_e32 v81, 16, v74
	v_and_b32_e32 v74, 0xffff0000, v74
	s_waitcnt lgkmcnt(1)
	v_mul_f32_e32 v74, v67, v74
	v_fmac_f32_e32 v74, v66, v81
	v_lshlrev_b32_e32 v66, 16, v75
	v_fmac_f32_e32 v74, v68, v66
	v_and_b32_e32 v66, 0xffff0000, v75
	v_fmac_f32_e32 v74, v69, v66
	v_lshlrev_b32_e32 v66, 16, v76
	s_waitcnt lgkmcnt(0)
	v_fmac_f32_e32 v74, v70, v66
	v_and_b32_e32 v66, 0xffff0000, v76
	v_fmac_f32_e32 v74, v71, v66
	v_lshlrev_b32_e32 v66, 16, v77
	v_fmac_f32_e32 v74, v72, v66
	v_and_b32_e32 v66, 0xffff0000, v77
	v_fmac_f32_e32 v74, v73, v66
	ds_read_b128 v[66:69], v65 offset:96
	ds_read_b128 v[70:73], v65 offset:112
	v_and_b32_e32 v75, 0xffff0000, v82
	v_lshlrev_b32_e32 v65, 16, v82
	v_add_f32_e32 v74, v79, v74
	s_waitcnt lgkmcnt(1)
	v_mul_f32_e32 v67, v67, v75
	v_fmac_f32_e32 v67, v66, v65
	v_lshlrev_b32_e32 v65, 16, v83
	v_fmac_f32_e32 v67, v68, v65
	v_and_b32_e32 v65, 0xffff0000, v83
	v_fmac_f32_e32 v67, v69, v65
	v_lshlrev_b32_e32 v65, 16, v84
	s_waitcnt lgkmcnt(0)
	v_fmac_f32_e32 v67, v70, v65
	v_and_b32_e32 v65, 0xffff0000, v84
	v_fmac_f32_e32 v67, v71, v65
	v_lshlrev_b32_e32 v65, 16, v85
	v_fmac_f32_e32 v67, v72, v65
	v_and_b32_e32 v65, 0xffff0000, v85
	v_fmac_f32_e32 v67, v73, v65
	v_add_f32_e32 v65, v74, v67
	v_xor_b32_e32 v66, 1, v232
	v_add_u32_e32 v67, 64, v126
	v_cmp_lt_i32_e32 vcc, v66, v67
	s_nop 1
	v_cndmask_b32_e32 v66, v232, v66, vcc
	v_lshlrev_b32_e32 v66, 2, v66
	ds_bpermute_b32 v66, v66, v65
	s_waitcnt lgkmcnt(0)
	v_add_f32_e32 v65, v65, v66
	v_xor_b32_e32 v66, 2, v232
	v_cmp_lt_i32_e32 vcc, v66, v67
	s_nop 1
	v_cndmask_b32_e32 v66, v232, v66, vcc
	v_lshlrev_b32_e32 v66, 2, v66
	ds_bpermute_b32 v66, v66, v65
	v_cmp_eq_u32_e32 vcc, 0, v78
	s_and_saveexec_b64 s[0:1], vcc
	s_cbranch_execz .LBB0_153
	v_lshl_add_u32 v64, v64, 2, 0
	s_waitcnt lgkmcnt(0)
	v_add_f32_e32 v65, v65, v66
	v_add_u32_e32 v64, 0x20b00, v64
	ds_write_b32 v64, v65

; DI unsigned pk2(float lo, float hi) { f32x2n v = {lo, hi}; bf16x2n b = __builtin_convertvector(v, bf16x2n); return __builtin_bit_cast(unsigned, b); }
; DI float frcp(float x) { return __builtin_amdgcn_rcpf(x); }
; DI void merge_phase(bf16_t* QKV, const float* LSE, int G, int bid) {
;     ...
;     for (int tl0 = gw; tl0 < TH; tl0 += 4 * NGW) {
;         u32x4 a[4][2], b[4][2], c[4][2]; float l0[4], l1[4], l2[4]; bf16_t* p0[4];
; #pragma unroll
;         for (int r = 0; r < 4; ++r) { const int tl = tl0 + r * NGW; const int bl = tl >> 13, t = tl & 8191;
;             const int pr0 = tl, pr1 = (bl << 13) + ((t & 3) << 11) + (t >> 2), pr2 = (bl << 13) + ((t & 15) << 9) + (t >> 4);
;             l0[r] = LSE[((size_t)0 * TH + pr0) * 16 + h]; l1[r] = LSE[((size_t)1 * TH + pr1) * 16 + h]; l2[r] = LSE[((size_t)2 * TH + pr2) * 16 + h];
;             p0[r] = QKV + (size_t)pr0 * 1024 + col; const bf16_t* p1 = QKV + SEC + (size_t)pr1 * 1024 + col; const bf16_t* p2 = QKV + 2 * SEC + (size_t)pr2 * 1024 + col;
; #pragma unroll
;             for (int q = 0; q < 2; ++q) { a[r][q] = *(const u32x4*)(p0[r] + 8 * q); b[r][q] = *(const u32x4*)(p1 + 8 * q); c[r][q] = *(const u32x4*)(p2 + 8 * q); } }
; #pragma unroll
;         for (int r = 0; r < 4; ++r) {
;             const float m = fmaxf(l0[r], fmaxf(l1[r], l2[r])); float w0 = __expf(l0[r] - m), w1 = __expf(l1[r] - m), w2 = __expf(l2[r] - m); const float is = frcp(w0 + w1 + w2); w0 *= is; w1 *= is; w2 *= is;
; #pragma unroll
;             for (int q = 0; q < 2; ++q) { const u32x4 A = a[r][q], B = b[r][q], C = c[r][q]; u32x4 o;
;                 o.x = pk2(w0 * bflo(A.x) + w1 * bflo(B.x) + w2 * bflo(C.x), w0 * bfhi(A.x) + w1 * bfhi(B.x) + w2 * bfhi(C.x));
;                 o.y = pk2(w0 * bflo(A.y) + w1 * bflo(B.y) + w2 * bflo(C.y), w0 * bfhi(A.y) + w1 * bfhi(B.y) + w2 * bfhi(C.y));
;                 o.z = pk2(w0 * bflo(A.z) + w1 * bflo(B.z) + w2 * bflo(C.z), w0 * bfhi(A.z) + w1 * bfhi(B.z) + w2 * bfhi(C.z));
;                 o.w = pk2(w0 * bflo(A.w) + w1 * bflo(B.w) + w2 * bflo(C.w), w0 * bfhi(A.w) + w1 * bfhi(B.w) + w2 * bfhi(C.w));
;                 *(u32x4*)(p0[r] + 8 * q) = o; }
;         }
.LBB0_308:
	v_and_b32_e32 v74, 0x1800, v117
	v_and_b32_e32 v1, 0xffffe000, v72
	v_bfe_u32 v0, v72, 2, 11
	v_ashrrev_i32_e32 v73, 31, v72
	v_or3_b32 v0, v0, v1, v74
	v_and_b32_e32 v49, 0x1e00, v116
	v_bfe_u32 v2, v72, 4, 9
	v_lshlrev_b64 v[4:5], 6, v[72:73]
	v_or3_b32 v2, v1, v2, v49
	v_lshl_add_u64 v[4:5], v[96:97], 0, v[4:5]
	v_ashrrev_i32_e32 v1, 31, v0
	global_load_dword v118, v[4:5], off
	v_lshlrev_b64 v[4:5], 6, v[0:1]
	v_lshl_add_u64 v[4:5], s[20:21], 0, v[4:5]
	v_lshl_add_u64 v[4:5], v[4:5], 0, v[112:113]
	v_add_co_u32_e32 v4, vcc, s41, v4
	v_ashrrev_i32_e32 v3, 31, v2
	s_nop 0
	v_addc_co_u32_e32 v5, vcc, 0, v5, vcc
	global_load_dword v119, v[4:5], off
	v_lshlrev_b64 v[4:5], 6, v[2:3]
	v_lshl_add_u64 v[4:5], s[20:21], 0, v[4:5]
	v_lshl_add_u64 v[4:5], v[4:5], 0, v[112:113]
	v_add_co_u32_e32 v4, vcc, s42, v4
	v_add_u32_e32 v104, s33, v72
	s_nop 0
	v_addc_co_u32_e32 v5, vcc, 0, v5, vcc
	global_load_dword v120, v[4:5], off
	v_lshlrev_b64 v[4:5], 11, v[72:73]
	v_lshlrev_b64 v[0:1], 11, v[0:1]
	v_lshlrev_b64 v[2:3], 11, v[2:3]
	v_ashrrev_i32_e32 v105, 31, v104
	v_lshl_add_u64 v[106:107], v[98:99], 0, v[4:5]
	v_lshl_add_u64 v[0:1], v[100:101], 0, v[0:1]
	v_lshl_add_u64 v[12:13], v[102:103], 0, v[2:3]
	v_lshlrev_b64 v[28:29], 6, v[104:105]
	global_load_dwordx4 v[4:7], v[106:107], off offset:16 nt
	global_load_dwordx4 v[16:19], v[106:107], off nt
	global_load_dwordx4 v[8:11], v[0:1], off offset:16 nt
	global_load_dwordx4 v[20:23], v[0:1], off nt
	s_nop 0
	global_load_dwordx4 v[0:3], v[12:13], off offset:16 nt
	s_nop 0
	global_load_dwordx4 v[12:15], v[12:13], off nt
	v_lshl_add_u64 v[28:29], v[96:97], 0, v[28:29]
	global_load_dword v121, v[28:29], off
	v_and_b32_e32 v25, 0xffffe000, v104
	v_bfe_u32 v24, v104, 2, 11
	v_add_u32_e32 v26, s99, v116
	v_or3_b32 v24, v74, v24, v25
	v_and_b32_e32 v26, 0x1e00, v26
	v_bfe_u32 v27, v104, 4, 9
	v_or3_b32 v26, v26, v27, v25
	v_ashrrev_i32_e32 v25, 31, v24
	v_lshlrev_b64 v[28:29], 6, v[24:25]
	v_lshl_add_u64 v[28:29], s[20:21], 0, v[28:29]
	v_lshl_add_u64 v[28:29], v[28:29], 0, v[112:113]
	v_add_co_u32_e32 v28, vcc, s41, v28
	v_ashrrev_i32_e32 v27, 31, v26
	s_nop 0
	v_addc_co_u32_e32 v29, vcc, 0, v29, vcc
	global_load_dword v128, v[28:29], off
	v_lshlrev_b64 v[28:29], 6, v[26:27]
	v_lshl_add_u64 v[28:29], s[20:21], 0, v[28:29]
	v_lshl_add_u64 v[28:29], v[28:29], 0, v[112:113]
	v_add_co_u32_e32 v28, vcc, s42, v28
	v_lshlrev_b64 v[24:25], 11, v[24:25]
	s_nop 0
	v_addc_co_u32_e32 v29, vcc, 0, v29, vcc
	global_load_dword v129, v[28:29], off
	v_lshlrev_b64 v[28:29], 11, v[104:105]
	v_lshlrev_b64 v[26:27], 11, v[26:27]
	v_lshl_add_u64 v[108:109], v[98:99], 0, v[28:29]
	v_lshl_add_u64 v[24:25], v[100:101], 0, v[24:25]
	v_lshl_add_u64 v[36:37], v[102:103], 0, v[26:27]
	global_load_dwordx4 v[28:31], v[108:109], off offset:16 nt
	global_load_dwordx4 v[40:43], v[108:109], off nt
	global_load_dwordx4 v[32:35], v[24:25], off offset:16 nt
	global_load_dwordx4 v[44:47], v[24:25], off nt
	s_nop 0
	global_load_dwordx4 v[24:27], v[36:37], off offset:16 nt
	s_nop 0
	global_load_dwordx4 v[36:39], v[36:37], off nt
	v_add_u32_e32 v48, s98, v72
	v_and_b32_e32 v51, 0xffffe000, v48
	v_bfe_u32 v52, v48, 4, 9
	v_bfe_u32 v50, v48, 2, 11
	v_or3_b32 v52, v49, v52, v51
	v_ashrrev_i32_e32 v49, 31, v48
	v_or3_b32 v50, v74, v50, v51
	v_lshlrev_b64 v[54:55], 6, v[48:49]
	v_lshl_add_u64 v[54:55], v[96:97], 0, v[54:55]
	v_ashrrev_i32_e32 v51, 31, v50
	global_load_dword v105, v[54:55], off
	v_lshlrev_b64 v[54:55], 6, v[50:51]
	v_lshl_add_u64 v[54:55], s[20:21], 0, v[54:55]
	v_lshl_add_u64 v[54:55], v[54:55], 0, v[112:113]
	v_add_co_u32_e32 v54, vcc, s41, v54
	v_ashrrev_i32_e32 v53, 31, v52
	s_nop 0
	v_addc_co_u32_e32 v55, vcc, 0, v55, vcc
	global_load_dword v130, v[54:55], off
	v_lshlrev_b64 v[54:55], 6, v[52:53]
	v_lshl_add_u64 v[54:55], s[20:21], 0, v[54:55]
	v_lshl_add_u64 v[54:55], v[54:55], 0, v[112:113]
	v_add_co_u32_e32 v54, vcc, s42, v54
	v_add_u32_e32 v72, s40, v72
	s_nop 0
	v_addc_co_u32_e32 v55, vcc, 0, v55, vcc
	global_load_dword v131, v[54:55], off
	v_and_b32_e32 v73, 0xffffe000, v72
	v_bfe_u32 v75, v72, 2, 11
	s_mul_i32 s2, s3, 0x3000
	v_or3_b32 v74, v74, v75, v73
	v_add_u32_e32 v75, s2, v116
	v_and_b32_e32 v75, 0x1e00, v75
	v_bfe_u32 v76, v72, 4, 9
	s_waitcnt vmcnt(18)
	v_max3_f32 v124, v118, v119, v120
	v_sub_f32_e32 v118, v118, v124
	v_mul_f32_e32 v118, 0x3fb8aa3b, v118
	v_exp_f32_e32 v123, v118
	v_sub_f32_e32 v118, v119, v124
	v_mul_f32_e32 v118, 0x3fb8aa3b, v118
	v_exp_f32_e32 v122, v118
	v_sub_f32_e32 v118, v120, v124
	v_mul_f32_e32 v118, 0x3fb8aa3b, v118
	v_exp_f32_e32 v119, v118
	v_add_f32_e32 v118, v123, v122
	s_waitcnt vmcnt(16)
	v_lshlrev_b32_e32 v124, 16, v16
	s_waitcnt vmcnt(14)
	v_and_b32_e32 v125, 0xffff0000, v20
	v_add_f32_e32 v118, v119, v118
	v_rcp_f32_e32 v118, v118
	s_waitcnt vmcnt(12)
	v_lshlrev_b32_e32 v126, 16, v12
	v_and_b32_e32 v127, 0xffff0000, v12
	v_lshlrev_b64 v[48:49], 11, v[48:49]
	v_mul_f32_e32 v120, v119, v118
	v_pk_mul_f32 v[118:119], v[122:123], v[118:119] op_sel_hi:[1,0]
	v_lshlrev_b32_e32 v122, 16, v20
	v_and_b32_e32 v123, 0xffff0000, v16
	v_pk_mul_f32 v[124:125], v[118:119], v[124:125] op_sel:[1,0] op_sel_hi:[0,1]
	v_pk_fma_f32 v[122:123], v[118:119], v[122:123], v[124:125]
	v_or3_b32 v76, v75, v76, v73
	v_ashrrev_i32_e32 v73, 31, v72
	s_waitcnt vmcnt(11)
; DI unsigned pk2(float lo, float hi) { f32x2n v = {lo, hi}; bf16x2n b = __builtin_convertvector(v, bf16x2n); return __builtin_bit_cast(unsigned, b); }
; DI float frcp(float x) { return __builtin_amdgcn_rcpf(x); }
; DI void merge_phase(bf16_t* QKV, const float* LSE, int G, int bid) {
;     ...
;     for (int tl0 = gw; tl0 < TH; tl0 += 4 * NGW) {
;         u32x4 a[4][2], b[4][2], c[4][2]; float l0[4], l1[4], l2[4]; bf16_t* p0[4];
; #pragma unroll
;         for (int r = 0; r < 4; ++r) { const int tl = tl0 + r * NGW; const int bl = tl >> 13, t = tl & 8191;
;             const int pr0 = tl, pr1 = (bl << 13) + ((t & 3) << 11) + (t >> 2), pr2 = (bl << 13) + ((t & 15) << 9) + (t >> 4);
;             l0[r] = LSE[((size_t)0 * TH + pr0) * 16 + h]; l1[r] = LSE[((size_t)1 * TH + pr1) * 16 + h]; l2[r] = LSE[((size_t)2 * TH + pr2) * 16 + h];
;             p0[r] = QKV + (size_t)pr0 * 1024 + col; const bf16_t* p1 = QKV + SEC + (size_t)pr1 * 1024 + col; const bf16_t* p2 = QKV + 2 * SEC + (size_t)pr2 * 1024 + col;
; #pragma unroll
;             for (int q = 0; q < 2; ++q) { a[r][q] = *(const u32x4*)(p0[r] + 8 * q); b[r][q] = *(const u32x4*)(p1 + 8 * q); c[r][q] = *(const u32x4*)(p2 + 8 * q); } }
; #pragma unroll
;         for (int r = 0; r < 4; ++r) {
;             const float m = fmaxf(l0[r], fmaxf(l1[r], l2[r])); float w0 = __expf(l0[r] - m), w1 = __expf(l1[r] - m), w2 = __expf(l2[r] - m); const float is = frcp(w0 + w1 + w2); w0 *= is; w1 *= is; w2 *= is;
; #pragma unroll
;             for (int q = 0; q < 2; ++q) { const u32x4 A = a[r][q], B = b[r][q], C = c[r][q]; u32x4 o;
;                 o.x = pk2(w0 * bflo(A.x) + w1 * bflo(B.x) + w2 * bflo(C.x), w0 * bfhi(A.x) + w1 * bfhi(B.x) + w2 * bfhi(C.x));
;                 o.y = pk2(w0 * bflo(A.y) + w1 * bflo(B.y) + w2 * bflo(C.y), w0 * bfhi(A.y) + w1 * bfhi(B.y) + w2 * bfhi(C.y));
;                 o.z = pk2(w0 * bflo(A.z) + w1 * bflo(B.z) + w2 * bflo(C.z), w0 * bfhi(A.z) + w1 * bfhi(B.z) + w2 * bfhi(C.z));
;                 o.w = pk2(w0 * bflo(A.w) + w1 * bflo(B.w) + w2 * bflo(C.w), w0 * bfhi(A.w) + w1 * bfhi(B.w) + w2 * bfhi(C.w));
;                 *(u32x4*)(p0[r] + 8 * q) = o; }
;         }
	v_pk_fma_f32 v[122:123], v[120:121], v[126:127], v[122:123] op_sel_hi:[0,1,1]
	v_lshl_add_u64 v[110:111], v[98:99], 0, v[48:49]
	v_lshlrev_b64 v[48:49], 11, v[50:51]
	v_lshlrev_b64 v[50:51], 11, v[52:53]
	v_lshlrev_b64 v[78:79], 6, v[72:73]
	v_cvt_pk_bf16_f32 v12, v122, v123
	v_and_b32_e32 v123, 0xffff0000, v17
	v_lshlrev_b32_e32 v16, 16, v17
	v_and_b32_e32 v17, 0xffff0000, v21
	v_lshl_add_u64 v[48:49], v[100:101], 0, v[48:49]
	v_lshl_add_u64 v[60:61], v[102:103], 0, v[50:51]
	v_lshl_add_u64 v[78:79], v[96:97], 0, v[78:79]
	v_ashrrev_i32_e32 v75, 31, v74
	v_lshlrev_b32_e32 v122, 16, v21
	v_pk_mul_f32 v[16:17], v[118:119], v[16:17] op_sel:[1,0] op_sel_hi:[0,1]
	global_load_dwordx4 v[52:55], v[110:111], off offset:16 nt
	global_load_dwordx4 v[64:67], v[110:111], off nt
	global_load_dwordx4 v[56:59], v[48:49], off offset:16 nt
	global_load_dwordx4 v[68:71], v[48:49], off nt
	s_nop 0
	global_load_dwordx4 v[48:51], v[60:61], off offset:16 nt
	s_nop 0
	global_load_dwordx4 v[60:63], v[60:61], off nt
	v_lshlrev_b32_e32 v20, 16, v13
	global_load_dword v132, v[78:79], off
	v_lshlrev_b64 v[78:79], 6, v[74:75]
	v_and_b32_e32 v21, 0xffff0000, v13
	v_pk_fma_f32 v[16:17], v[118:119], v[122:123], v[16:17]
	v_lshl_add_u64 v[78:79], s[20:21], 0, v[78:79]
	v_pk_fma_f32 v[16:17], v[120:121], v[20:21], v[16:17] op_sel_hi:[0,1,1]
	v_lshlrev_b32_e32 v20, 16, v18
	v_and_b32_e32 v21, 0xffff0000, v22
	v_lshl_add_u64 v[78:79], v[78:79], 0, v[112:113]
	v_cvt_pk_bf16_f32 v13, v16, v17
	v_lshlrev_b32_e32 v16, 16, v22
	v_and_b32_e32 v17, 0xffff0000, v18
	v_pk_mul_f32 v[20:21], v[118:119], v[20:21] op_sel:[1,0] op_sel_hi:[0,1]
	v_add_co_u32_e32 v78, vcc, s41, v78
	v_lshlrev_b32_e32 v122, 16, v14
	v_and_b32_e32 v123, 0xffff0000, v14
	v_pk_fma_f32 v[16:17], v[118:119], v[16:17], v[20:21]
	v_addc_co_u32_e32 v79, vcc, 0, v79, vcc
	v_ashrrev_i32_e32 v77, 31, v76
	v_pk_fma_f32 v[16:17], v[120:121], v[122:123], v[16:17] op_sel_hi:[0,1,1]
	global_load_dword v133, v[78:79], off
	v_lshlrev_b64 v[78:79], 6, v[76:77]
	v_cvt_pk_bf16_f32 v14, v16, v17
	v_and_b32_e32 v17, 0xffff0000, v19
	v_lshlrev_b32_e32 v18, 16, v19
	v_and_b32_e32 v19, 0xffff0000, v23
	v_lshl_add_u64 v[78:79], s[20:21], 0, v[78:79]
	v_lshlrev_b32_e32 v16, 16, v23
	v_pk_mul_f32 v[18:19], v[118:119], v[18:19] op_sel:[1,0] op_sel_hi:[0,1]
	v_lshl_add_u64 v[78:79], v[78:79], 0, v[112:113]
	v_lshlrev_b64 v[72:73], 11, v[72:73]
	v_pk_fma_f32 v[16:17], v[118:119], v[16:17], v[18:19]
	v_lshlrev_b32_e32 v18, 16, v15
	v_and_b32_e32 v19, 0xffff0000, v15
	v_add_co_u32_e32 v78, vcc, s42, v78
	v_lshl_add_u64 v[114:115], v[98:99], 0, v[72:73]
	v_lshlrev_b64 v[72:73], 11, v[74:75]
	v_lshlrev_b64 v[74:75], 11, v[76:77]
	v_pk_fma_f32 v[16:17], v[120:121], v[18:19], v[16:17] op_sel_hi:[0,1,1]
	v_addc_co_u32_e32 v79, vcc, 0, v79, vcc
	v_lshl_add_u64 v[72:73], v[100:101], 0, v[72:73]
	s_waitcnt lgkmcnt(0)
	v_lshl_add_u64 v[84:85], v[102:103], 0, v[74:75]
	v_cvt_pk_bf16_f32 v15, v16, v17
	global_load_dword v134, v[78:79], off
	s_nop 0
	global_load_dwordx4 v[76:79], v[114:115], off offset:16 nt
	global_load_dwordx4 v[88:91], v[114:115], off nt
	global_load_dwordx4 v[80:83], v[72:73], off offset:16 nt
	global_load_dwordx4 v[92:95], v[72:73], off nt
	s_nop 0
	global_load_dwordx4 v[72:75], v[84:85], off offset:16 nt
	s_nop 0
	global_load_dwordx4 v[84:87], v[84:85], off nt
	s_add_i32 s2, s33, s33
	global_store_dwordx4 v[106:107], v[12:15], off nt
	s_add_i32 s2, s2, s33
	v_add_u32_e32 v116, s97, v116
	v_lshlrev_b32_e32 v14, 16, v4
	v_and_b32_e32 v15, 0xffff0000, v8
	v_lshlrev_b32_e32 v12, 16, v8
	v_and_b32_e32 v13, 0xffff0000, v4
	v_pk_mul_f32 v[14:15], v[118:119], v[14:15] op_sel:[1,0] op_sel_hi:[0,1]
	v_pk_fma_f32 v[12:13], v[118:119], v[12:13], v[14:15]
	v_lshlrev_b32_e32 v14, 16, v0
	v_and_b32_e32 v15, 0xffff0000, v0
	v_pk_fma_f32 v[12:13], v[120:121], v[14:15], v[12:13] op_sel_hi:[0,1,1]
	v_cvt_pk_bf16_f32 v0, v12, v13
	v_and_b32_e32 v13, 0xffff0000, v5
	v_lshlrev_b32_e32 v4, 16, v5
	v_and_b32_e32 v5, 0xffff0000, v9
	v_lshlrev_b32_e32 v12, 16, v9
	v_pk_mul_f32 v[4:5], v[118:119], v[4:5] op_sel:[1,0] op_sel_hi:[0,1]
	v_pk_fma_f32 v[4:5], v[118:119], v[12:13], v[4:5]
	v_lshlrev_b32_e32 v8, 16, v1
	v_and_b32_e32 v9, 0xffff0000, v1
	v_pk_fma_f32 v[4:5], v[120:121], v[8:9], v[4:5] op_sel_hi:[0,1,1]
	v_lshlrev_b32_e32 v8, 16, v6
	v_and_b32_e32 v9, 0xffff0000, v10
	v_cvt_pk_bf16_f32 v1, v4, v5
	v_lshlrev_b32_e32 v4, 16, v10
	v_and_b32_e32 v5, 0xffff0000, v6
	v_pk_mul_f32 v[8:9], v[118:119], v[8:9] op_sel:[1,0] op_sel_hi:[0,1]
	v_pk_fma_f32 v[4:5], v[118:119], v[4:5], v[8:9]
	v_lshlrev_b32_e32 v8, 16, v2
	v_and_b32_e32 v9, 0xffff0000, v2
	v_pk_fma_f32 v[4:5], v[120:121], v[8:9], v[4:5] op_sel_hi:[0,1,1]
	v_cvt_pk_bf16_f32 v2, v4, v5
	v_and_b32_e32 v5, 0xffff0000, v7
	v_lshlrev_b32_e32 v6, 16, v7
	v_and_b32_e32 v7, 0xffff0000, v11
	v_lshlrev_b32_e32 v4, 16, v11
	v_pk_mul_f32 v[6:7], v[118:119], v[6:7] op_sel:[1,0] op_sel_hi:[0,1]
	v_pk_fma_f32 v[4:5], v[118:119], v[4:5], v[6:7]
	v_lshlrev_b32_e32 v6, 16, v3
	v_and_b32_e32 v7, 0xffff0000, v3
	v_pk_fma_f32 v[4:5], v[120:121], v[6:7], v[4:5] op_sel_hi:[0,1,1]
	v_cvt_pk_bf16_f32 v3, v4, v5
	global_store_dwordx4 v[106:107], v[0:3], off offset:16 nt
	s_waitcnt vmcnt(20)
; DI unsigned pk2(float lo, float hi) { f32x2n v = {lo, hi}; bf16x2n b = __builtin_convertvector(v, bf16x2n); return __builtin_bit_cast(unsigned, b); }
; DI float frcp(float x) { return __builtin_amdgcn_rcpf(x); }
; DI void merge_phase(bf16_t* QKV, const float* LSE, int G, int bid) {
;     ...
;             const float m = fmaxf(l0[r], fmaxf(l1[r], l2[r])); float w0 = __expf(l0[r] - m), w1 = __expf(l1[r] - m), w2 = __expf(l2[r] - m); const float is = frcp(w0 + w1 + w2); w0 *= is; w1 *= is; w2 *= is;
; #pragma unroll
;             for (int q = 0; q < 2; ++q) { const u32x4 A = a[r][q], B = b[r][q], C = c[r][q]; u32x4 o;
;                 o.x = pk2(w0 * bflo(A.x) + w1 * bflo(B.x) + w2 * bflo(C.x), w0 * bfhi(A.x) + w1 * bfhi(B.x) + w2 * bfhi(C.x));
;                 o.y = pk2(w0 * bflo(A.y) + w1 * bflo(B.y) + w2 * bflo(C.y), w0 * bfhi(A.y) + w1 * bfhi(B.y) + w2 * bfhi(C.y));
;                 o.z = pk2(w0 * bflo(A.z) + w1 * bflo(B.z) + w2 * bflo(C.z), w0 * bfhi(A.z) + w1 * bfhi(B.z) + w2 * bfhi(C.z));
;                 o.w = pk2(w0 * bflo(A.w) + w1 * bflo(B.w) + w2 * bflo(C.w), w0 * bfhi(A.w) + w1 * bfhi(B.w) + w2 * bfhi(C.w));
;                 *(u32x4*)(p0[r] + 8 * q) = o; }
	v_lshlrev_b32_e32 v8, 16, v36
	v_and_b32_e32 v9, 0xffff0000, v36
	v_max3_f32 v2, v121, v128, v129
	v_sub_f32_e32 v0, v121, v2
	v_mul_f32_e32 v0, 0x3fb8aa3b, v0
	v_exp_f32_e32 v1, v0
	v_sub_f32_e32 v0, v128, v2
	v_mul_f32_e32 v0, 0x3fb8aa3b, v0
	v_sub_f32_e32 v2, v129, v2
	v_exp_f32_e32 v0, v0
	v_mul_f32_e32 v2, 0x3fb8aa3b, v2
	v_exp_f32_e32 v3, v2
	v_lshlrev_b32_e32 v10, 16, v37
	v_add_f32_e32 v2, v1, v0
	v_and_b32_e32 v11, 0xffff0000, v37
	v_add_f32_e32 v2, v3, v2
	v_rcp_f32_e32 v2, v2
	v_add_u32_e32 v117, s34, v117
	v_mul_f32_e32 v4, v3, v2
	v_pk_mul_f32 v[6:7], v[0:1], v[2:3] op_sel_hi:[1,0]
	v_lshlrev_b32_e32 v2, 16, v40
	v_and_b32_e32 v3, 0xffff0000, v44
	v_lshlrev_b32_e32 v0, 16, v44
	v_and_b32_e32 v1, 0xffff0000, v40
	v_pk_mul_f32 v[2:3], v[6:7], v[2:3] op_sel:[1,0] op_sel_hi:[0,1]
	v_pk_fma_f32 v[0:1], v[6:7], v[0:1], v[2:3]
	v_lshlrev_b32_e32 v2, 16, v45
	v_pk_fma_f32 v[0:1], v[4:5], v[8:9], v[0:1] op_sel_hi:[0,1,1]
	v_lshlrev_b32_e32 v8, 16, v41
	v_and_b32_e32 v9, 0xffff0000, v45
	v_and_b32_e32 v3, 0xffff0000, v41
	v_pk_mul_f32 v[8:9], v[6:7], v[8:9] op_sel:[1,0] op_sel_hi:[0,1]
	v_pk_fma_f32 v[2:3], v[6:7], v[2:3], v[8:9]
	v_lshlrev_b32_e32 v8, 16, v42
	v_pk_fma_f32 v[2:3], v[4:5], v[10:11], v[2:3] op_sel_hi:[0,1,1]
	v_and_b32_e32 v9, 0xffff0000, v46
	v_cvt_pk_bf16_f32 v0, v0, v1
	v_cvt_pk_bf16_f32 v1, v2, v3
	v_lshlrev_b32_e32 v2, 16, v46
	v_and_b32_e32 v3, 0xffff0000, v42
	v_pk_mul_f32 v[8:9], v[6:7], v[8:9] op_sel:[1,0] op_sel_hi:[0,1]
	v_lshlrev_b32_e32 v10, 16, v38
	v_and_b32_e32 v11, 0xffff0000, v38
	v_pk_fma_f32 v[2:3], v[6:7], v[2:3], v[8:9]
	v_lshlrev_b32_e32 v8, 16, v47
	v_pk_fma_f32 v[2:3], v[4:5], v[10:11], v[2:3] op_sel_hi:[0,1,1]
	v_lshlrev_b32_e32 v10, 16, v43
	v_and_b32_e32 v11, 0xffff0000, v47
	v_and_b32_e32 v9, 0xffff0000, v43
	v_pk_mul_f32 v[10:11], v[6:7], v[10:11] op_sel:[1,0] op_sel_hi:[0,1]
	v_pk_fma_f32 v[8:9], v[6:7], v[8:9], v[10:11]
	v_lshlrev_b32_e32 v10, 16, v39
	v_and_b32_e32 v11, 0xffff0000, v39
	v_pk_fma_f32 v[8:9], v[4:5], v[10:11], v[8:9] op_sel_hi:[0,1,1]
	v_cvt_pk_bf16_f32 v2, v2, v3
	v_cvt_pk_bf16_f32 v3, v8, v9
	global_store_dwordx4 v[108:109], v[0:3], off nt
	v_lshlrev_b32_e32 v8, 16, v29
	v_and_b32_e32 v9, 0xffff0000, v33
	v_lshlrev_b32_e32 v2, 16, v28
	v_and_b32_e32 v3, 0xffff0000, v32
	v_lshlrev_b32_e32 v0, 16, v32
	v_and_b32_e32 v1, 0xffff0000, v28
	v_pk_mul_f32 v[2:3], v[6:7], v[2:3] op_sel:[1,0] op_sel_hi:[0,1]
	v_pk_fma_f32 v[0:1], v[6:7], v[0:1], v[2:3]
	v_lshlrev_b32_e32 v2, 16, v24
	v_and_b32_e32 v3, 0xffff0000, v24
	v_pk_fma_f32 v[0:1], v[4:5], v[2:3], v[0:1] op_sel_hi:[0,1,1]
	v_lshlrev_b32_e32 v2, 16, v33
	v_and_b32_e32 v3, 0xffff0000, v29
	v_pk_mul_f32 v[8:9], v[6:7], v[8:9] op_sel:[1,0] op_sel_hi:[0,1]
	v_pk_fma_f32 v[2:3], v[6:7], v[2:3], v[8:9]
	v_lshlrev_b32_e32 v8, 16, v25
	v_and_b32_e32 v9, 0xffff0000, v25
	v_pk_fma_f32 v[2:3], v[4:5], v[8:9], v[2:3] op_sel_hi:[0,1,1]
	v_lshlrev_b32_e32 v8, 16, v30
	v_and_b32_e32 v9, 0xffff0000, v34
	v_cvt_pk_bf16_f32 v0, v0, v1
	v_cvt_pk_bf16_f32 v1, v2, v3
	v_lshlrev_b32_e32 v2, 16, v34
	v_and_b32_e32 v3, 0xffff0000, v30
	v_pk_mul_f32 v[8:9], v[6:7], v[8:9] op_sel:[1,0] op_sel_hi:[0,1]
	v_pk_fma_f32 v[2:3], v[6:7], v[2:3], v[8:9]
	v_lshlrev_b32_e32 v8, 16, v26
	v_and_b32_e32 v9, 0xffff0000, v26
	v_lshlrev_b32_e32 v10, 16, v31
	v_and_b32_e32 v11, 0xffff0000, v35
	v_pk_fma_f32 v[2:3], v[4:5], v[8:9], v[2:3] op_sel_hi:[0,1,1]
	v_lshlrev_b32_e32 v8, 16, v35
	v_and_b32_e32 v9, 0xffff0000, v31
	v_pk_mul_f32 v[10:11], v[6:7], v[10:11] op_sel:[1,0] op_sel_hi:[0,1]
	v_pk_fma_f32 v[6:7], v[6:7], v[8:9], v[10:11]
	v_lshlrev_b32_e32 v8, 16, v27
	v_and_b32_e32 v9, 0xffff0000, v27
	v_pk_fma_f32 v[4:5], v[4:5], v[8:9], v[6:7] op_sel_hi:[0,1,1]
	v_cvt_pk_bf16_f32 v2, v2, v3
	v_cvt_pk_bf16_f32 v3, v4, v5
	global_store_dwordx4 v[108:109], v[0:3], off offset:16 nt
	s_waitcnt vmcnt(13)
	v_lshlrev_b32_e32 v8, 16, v60
	v_and_b32_e32 v9, 0xffff0000, v60
	v_max3_f32 v2, v105, v130, v131
	v_sub_f32_e32 v0, v105, v2
	v_mul_f32_e32 v0, 0x3fb8aa3b, v0
	v_exp_f32_e32 v1, v0
	v_sub_f32_e32 v0, v130, v2
	v_mul_f32_e32 v0, 0x3fb8aa3b, v0
	v_sub_f32_e32 v2, v131, v2
	v_exp_f32_e32 v0, v0
	v_mul_f32_e32 v2, 0x3fb8aa3b, v2
	v_exp_f32_e32 v3, v2
	v_lshlrev_b32_e32 v10, 16, v61
	v_add_f32_e32 v2, v1, v0
	v_and_b32_e32 v11, 0xffff0000, v61
	v_add_f32_e32 v2, v3, v2
	v_rcp_f32_e32 v2, v2
	s_nop 0
	v_mul_f32_e32 v4, v3, v2
	v_pk_mul_f32 v[6:7], v[0:1], v[2:3] op_sel_hi:[1,0]
	v_lshlrev_b32_e32 v2, 16, v64
	v_and_b32_e32 v3, 0xffff0000, v68
	v_lshlrev_b32_e32 v0, 16, v68
	v_and_b32_e32 v1, 0xffff0000, v64
	v_pk_mul_f32 v[2:3], v[6:7], v[2:3] op_sel:[1,0] op_sel_hi:[0,1]
	v_pk_fma_f32 v[0:1], v[6:7], v[0:1], v[2:3]
	v_lshlrev_b32_e32 v2, 16, v69
	v_pk_fma_f32 v[0:1], v[4:5], v[8:9], v[0:1] op_sel_hi:[0,1,1]
	v_lshlrev_b32_e32 v8, 16, v65
	v_and_b32_e32 v9, 0xffff0000, v69
	v_and_b32_e32 v3, 0xffff0000, v65
	v_pk_mul_f32 v[8:9], v[6:7], v[8:9] op_sel:[1,0] op_sel_hi:[0,1]
	v_pk_fma_f32 v[2:3], v[6:7], v[2:3], v[8:9]
	v_lshlrev_b32_e32 v8, 16, v66
	v_pk_fma_f32 v[2:3], v[4:5], v[10:11], v[2:3] op_sel_hi:[0,1,1]
	v_and_b32_e32 v9, 0xffff0000, v70
	v_cvt_pk_bf16_f32 v0, v0, v1
	v_cvt_pk_bf16_f32 v1, v2, v3
	v_lshlrev_b32_e32 v2, 16, v70
	v_and_b32_e32 v3, 0xffff0000, v66
	v_pk_mul_f32 v[8:9], v[6:7], v[8:9] op_sel:[1,0] op_sel_hi:[0,1]
	v_lshlrev_b32_e32 v10, 16, v62
	v_and_b32_e32 v11, 0xffff0000, v62
	v_pk_fma_f32 v[2:3], v[6:7], v[2:3], v[8:9]
	v_lshlrev_b32_e32 v8, 16, v71
	v_pk_fma_f32 v[2:3], v[4:5], v[10:11], v[2:3] op_sel_hi:[0,1,1]
	v_lshlrev_b32_e32 v10, 16, v67
	v_and_b32_e32 v11, 0xffff0000, v71
	v_and_b32_e32 v9, 0xffff0000, v67
; DI unsigned pk2(float lo, float hi) { f32x2n v = {lo, hi}; bf16x2n b = __builtin_convertvector(v, bf16x2n); return __builtin_bit_cast(unsigned, b); }
; DI float frcp(float x) { return __builtin_amdgcn_rcpf(x); }
; DI void merge_phase(bf16_t* QKV, const float* LSE, int G, int bid) {
;     ...
;             const float m = fmaxf(l0[r], fmaxf(l1[r], l2[r])); float w0 = __expf(l0[r] - m), w1 = __expf(l1[r] - m), w2 = __expf(l2[r] - m); const float is = frcp(w0 + w1 + w2); w0 *= is; w1 *= is; w2 *= is;
; #pragma unroll
;             for (int q = 0; q < 2; ++q) { const u32x4 A = a[r][q], B = b[r][q], C = c[r][q]; u32x4 o;
;                 o.x = pk2(w0 * bflo(A.x) + w1 * bflo(B.x) + w2 * bflo(C.x), w0 * bfhi(A.x) + w1 * bfhi(B.x) + w2 * bfhi(C.x));
;                 o.y = pk2(w0 * bflo(A.y) + w1 * bflo(B.y) + w2 * bflo(C.y), w0 * bfhi(A.y) + w1 * bfhi(B.y) + w2 * bfhi(C.y));
;                 o.z = pk2(w0 * bflo(A.z) + w1 * bflo(B.z) + w2 * bflo(C.z), w0 * bfhi(A.z) + w1 * bfhi(B.z) + w2 * bfhi(C.z));
;                 o.w = pk2(w0 * bflo(A.w) + w1 * bflo(B.w) + w2 * bflo(C.w), w0 * bfhi(A.w) + w1 * bfhi(B.w) + w2 * bfhi(C.w));
;                 *(u32x4*)(p0[r] + 8 * q) = o; }
;         }
	v_pk_mul_f32 v[10:11], v[6:7], v[10:11] op_sel:[1,0] op_sel_hi:[0,1]
	v_pk_fma_f32 v[8:9], v[6:7], v[8:9], v[10:11]
	v_lshlrev_b32_e32 v10, 16, v63
	v_and_b32_e32 v11, 0xffff0000, v63
	v_pk_fma_f32 v[8:9], v[4:5], v[10:11], v[8:9] op_sel_hi:[0,1,1]
	v_cvt_pk_bf16_f32 v2, v2, v3
	v_cvt_pk_bf16_f32 v3, v8, v9
	global_store_dwordx4 v[110:111], v[0:3], off nt
	v_lshlrev_b32_e32 v8, 16, v53
	v_and_b32_e32 v9, 0xffff0000, v57
	v_lshlrev_b32_e32 v2, 16, v52
	v_and_b32_e32 v3, 0xffff0000, v56
	v_lshlrev_b32_e32 v0, 16, v56
	v_and_b32_e32 v1, 0xffff0000, v52
	v_pk_mul_f32 v[2:3], v[6:7], v[2:3] op_sel:[1,0] op_sel_hi:[0,1]
	v_pk_fma_f32 v[0:1], v[6:7], v[0:1], v[2:3]
	v_lshlrev_b32_e32 v2, 16, v48
	v_and_b32_e32 v3, 0xffff0000, v48
	v_pk_fma_f32 v[0:1], v[4:5], v[2:3], v[0:1] op_sel_hi:[0,1,1]
	v_lshlrev_b32_e32 v2, 16, v57
	v_and_b32_e32 v3, 0xffff0000, v53
	v_pk_mul_f32 v[8:9], v[6:7], v[8:9] op_sel:[1,0] op_sel_hi:[0,1]
	v_pk_fma_f32 v[2:3], v[6:7], v[2:3], v[8:9]
	v_lshlrev_b32_e32 v8, 16, v49
	v_and_b32_e32 v9, 0xffff0000, v49
	v_pk_fma_f32 v[2:3], v[4:5], v[8:9], v[2:3] op_sel_hi:[0,1,1]
	v_lshlrev_b32_e32 v8, 16, v54
	v_and_b32_e32 v9, 0xffff0000, v58
	v_cvt_pk_bf16_f32 v0, v0, v1
	v_cvt_pk_bf16_f32 v1, v2, v3
	v_lshlrev_b32_e32 v2, 16, v58
	v_and_b32_e32 v3, 0xffff0000, v54
	v_pk_mul_f32 v[8:9], v[6:7], v[8:9] op_sel:[1,0] op_sel_hi:[0,1]
	v_pk_fma_f32 v[2:3], v[6:7], v[2:3], v[8:9]
	v_lshlrev_b32_e32 v8, 16, v50
	v_and_b32_e32 v9, 0xffff0000, v50
	v_lshlrev_b32_e32 v10, 16, v55
	v_and_b32_e32 v11, 0xffff0000, v59
	v_pk_fma_f32 v[2:3], v[4:5], v[8:9], v[2:3] op_sel_hi:[0,1,1]
	v_lshlrev_b32_e32 v8, 16, v59
	v_and_b32_e32 v9, 0xffff0000, v55
	v_pk_mul_f32 v[10:11], v[6:7], v[10:11] op_sel:[1,0] op_sel_hi:[0,1]
	v_pk_fma_f32 v[6:7], v[6:7], v[8:9], v[10:11]
	v_lshlrev_b32_e32 v8, 16, v51
	v_and_b32_e32 v9, 0xffff0000, v51
	v_pk_fma_f32 v[4:5], v[4:5], v[8:9], v[6:7] op_sel_hi:[0,1,1]
	v_cvt_pk_bf16_f32 v2, v2, v3
	v_cvt_pk_bf16_f32 v3, v4, v5
	global_store_dwordx4 v[110:111], v[0:3], off offset:16 nt
	s_waitcnt vmcnt(6)
	v_lshlrev_b32_e32 v8, 16, v84
	v_and_b32_e32 v9, 0xffff0000, v84
	v_max3_f32 v2, v132, v133, v134
	v_sub_f32_e32 v0, v132, v2
	v_mul_f32_e32 v0, 0x3fb8aa3b, v0
	v_exp_f32_e32 v1, v0
	v_sub_f32_e32 v0, v133, v2
	v_mul_f32_e32 v0, 0x3fb8aa3b, v0
	v_sub_f32_e32 v2, v134, v2
	v_exp_f32_e32 v0, v0
	v_mul_f32_e32 v2, 0x3fb8aa3b, v2
	v_exp_f32_e32 v3, v2
	v_lshlrev_b32_e32 v10, 16, v85
	v_add_f32_e32 v2, v1, v0
	v_and_b32_e32 v11, 0xffff0000, v85
	v_add_f32_e32 v2, v3, v2
	v_rcp_f32_e32 v2, v2
	s_nop 0
	v_mul_f32_e32 v4, v3, v2
	v_pk_mul_f32 v[6:7], v[0:1], v[2:3] op_sel_hi:[1,0]
	v_lshlrev_b32_e32 v2, 16, v88
	v_and_b32_e32 v3, 0xffff0000, v92
	v_lshlrev_b32_e32 v0, 16, v92
	v_and_b32_e32 v1, 0xffff0000, v88
	v_pk_mul_f32 v[2:3], v[6:7], v[2:3] op_sel:[1,0] op_sel_hi:[0,1]
	v_pk_fma_f32 v[0:1], v[6:7], v[0:1], v[2:3]
	v_lshlrev_b32_e32 v2, 16, v93
	v_pk_fma_f32 v[0:1], v[4:5], v[8:9], v[0:1] op_sel_hi:[0,1,1]
	v_lshlrev_b32_e32 v8, 16, v89
	v_and_b32_e32 v9, 0xffff0000, v93
	v_and_b32_e32 v3, 0xffff0000, v89
	v_pk_mul_f32 v[8:9], v[6:7], v[8:9] op_sel:[1,0] op_sel_hi:[0,1]
	v_pk_fma_f32 v[2:3], v[6:7], v[2:3], v[8:9]
	v_lshlrev_b32_e32 v8, 16, v90
	v_pk_fma_f32 v[2:3], v[4:5], v[10:11], v[2:3] op_sel_hi:[0,1,1]
	v_and_b32_e32 v9, 0xffff0000, v94
	v_cvt_pk_bf16_f32 v0, v0, v1
	v_cvt_pk_bf16_f32 v1, v2, v3
	v_lshlrev_b32_e32 v2, 16, v94
	v_and_b32_e32 v3, 0xffff0000, v90
	v_pk_mul_f32 v[8:9], v[6:7], v[8:9] op_sel:[1,0] op_sel_hi:[0,1]
	v_lshlrev_b32_e32 v10, 16, v86
	v_and_b32_e32 v11, 0xffff0000, v86
	v_pk_fma_f32 v[2:3], v[6:7], v[2:3], v[8:9]
	v_lshlrev_b32_e32 v8, 16, v95
	v_pk_fma_f32 v[2:3], v[4:5], v[10:11], v[2:3] op_sel_hi:[0,1,1]
	v_lshlrev_b32_e32 v10, 16, v91
	v_and_b32_e32 v11, 0xffff0000, v95
	v_and_b32_e32 v9, 0xffff0000, v91
	v_pk_mul_f32 v[10:11], v[6:7], v[10:11] op_sel:[1,0] op_sel_hi:[0,1]
	v_pk_fma_f32 v[8:9], v[6:7], v[8:9], v[10:11]
	v_lshlrev_b32_e32 v10, 16, v87
	v_and_b32_e32 v11, 0xffff0000, v87
	v_pk_fma_f32 v[8:9], v[4:5], v[10:11], v[8:9] op_sel_hi:[0,1,1]
	v_cvt_pk_bf16_f32 v2, v2, v3
	v_cvt_pk_bf16_f32 v3, v8, v9
	global_store_dwordx4 v[114:115], v[0:3], off nt
	v_lshlrev_b32_e32 v8, 16, v77
	v_and_b32_e32 v9, 0xffff0000, v81
	v_lshlrev_b32_e32 v2, 16, v76
	v_and_b32_e32 v3, 0xffff0000, v80
	v_lshlrev_b32_e32 v0, 16, v80
	v_and_b32_e32 v1, 0xffff0000, v76
	v_pk_mul_f32 v[2:3], v[6:7], v[2:3] op_sel:[1,0] op_sel_hi:[0,1]
	v_pk_fma_f32 v[0:1], v[6:7], v[0:1], v[2:3]
	v_lshlrev_b32_e32 v2, 16, v72
	v_and_b32_e32 v3, 0xffff0000, v72
	v_pk_fma_f32 v[0:1], v[4:5], v[2:3], v[0:1] op_sel_hi:[0,1,1]
	v_lshlrev_b32_e32 v2, 16, v81
	v_and_b32_e32 v3, 0xffff0000, v77
	v_pk_mul_f32 v[8:9], v[6:7], v[8:9] op_sel:[1,0] op_sel_hi:[0,1]
	v_pk_fma_f32 v[2:3], v[6:7], v[2:3], v[8:9]
	v_lshlrev_b32_e32 v8, 16, v73
	v_and_b32_e32 v9, 0xffff0000, v73
	v_pk_fma_f32 v[2:3], v[4:5], v[8:9], v[2:3] op_sel_hi:[0,1,1]
	v_lshlrev_b32_e32 v8, 16, v78
	v_and_b32_e32 v9, 0xffff0000, v82
	v_cvt_pk_bf16_f32 v0, v0, v1
	v_cvt_pk_bf16_f32 v1, v2, v3
	v_lshlrev_b32_e32 v2, 16, v82
	v_and_b32_e32 v3, 0xffff0000, v78
	v_pk_mul_f32 v[8:9], v[6:7], v[8:9] op_sel:[1,0] op_sel_hi:[0,1]
	v_pk_fma_f32 v[2:3], v[6:7], v[2:3], v[8:9]
	v_lshlrev_b32_e32 v8, 16, v74
	v_and_b32_e32 v9, 0xffff0000, v74
	v_lshlrev_b32_e32 v10, 16, v79
	v_and_b32_e32 v11, 0xffff0000, v83
	v_pk_fma_f32 v[2:3], v[4:5], v[8:9], v[2:3] op_sel_hi:[0,1,1]
	v_lshlrev_b32_e32 v8, 16, v83
	v_and_b32_e32 v9, 0xffff0000, v79
	v_pk_mul_f32 v[10:11], v[6:7], v[10:11] op_sel:[1,0] op_sel_hi:[0,1]
	v_pk_fma_f32 v[6:7], v[6:7], v[8:9], v[10:11]
	v_lshlrev_b32_e32 v8, 16, v75
	v_and_b32_e32 v9, 0xffff0000, v75
	v_add_u32_e32 v72, s2, v104
	s_movk_i32 s2, 0x3fff
	v_pk_fma_f32 v[4:5], v[4:5], v[8:9], v[6:7] op_sel_hi:[0,1,1]
	v_cmp_lt_i32_e32 vcc, s2, v72
	v_cvt_pk_bf16_f32 v2, v2, v3
	v_cvt_pk_bf16_f32 v3, v4, v5
	s_or_b64 s[38:39], vcc, s[38:39]
	global_store_dwordx4 v[114:115], v[0:3], off offset:16 nt
	s_andn2_b64 exec, exec, s[38:39]
	s_cbranch_execnz .LBB0_308
